# P0: win_sample copy loop and sample-window K/V^T conversion loop hand-batched 8 deep (were 1 element per vmcnt(0) round trip); plus NSA epilogue hoists
# baseline (speedup 1.0000x reference)
.LBB0_201:
	s_waitcnt lgkmcnt(0)
	s_mov_b64 s[86:87], exec
.Lp0_wc_loop:
	v_mov_b32_e32 v201, v1
	v_mul_hi_i32 v226, v201, s3
	v_add_u32_e32 v226, v226, v201
	v_lshrrev_b32_e32 v227, 31, v226
	v_ashrrev_i32_e32 v226, 15, v226
	v_add_u32_e32 v226, v226, v227
	v_mul_i32_i24_e32 v227, 0xfe00, v226
	v_sub_u32_e32 v227, v201, v227
	v_lshlrev_b32_e32 v226, 20, v226
	v_lshl_add_u32 v209, v227, 4, v226
	v_cmp_ge_i32_e64 s[50:51], s12, v201
	s_and_b64 s[50:51], s[50:51], s[86:87]
	s_mov_b64 exec, s[50:51]
	v_add_u32_e32 v228, 0x2000, v209
	global_load_dwordx4 v[164:167], v228, s[6:7]
	s_mov_b64 exec, s[86:87]
	v_add_u32_e32 v202, s16, v201
	v_mul_hi_i32 v226, v202, s3
	v_add_u32_e32 v226, v226, v202
	v_lshrrev_b32_e32 v227, 31, v226
	v_ashrrev_i32_e32 v226, 15, v226
	v_add_u32_e32 v226, v226, v227
	v_mul_i32_i24_e32 v227, 0xfe00, v226
	v_sub_u32_e32 v227, v202, v227
	v_lshlrev_b32_e32 v226, 20, v226
	v_lshl_add_u32 v210, v227, 4, v226
	v_cmp_ge_i32_e64 s[52:53], s12, v202
	s_and_b64 s[52:53], s[52:53], s[86:87]
	s_mov_b64 exec, s[52:53]
	v_add_u32_e32 v228, 0x2000, v210
	global_load_dwordx4 v[168:171], v228, s[6:7]
	s_mov_b64 exec, s[86:87]
	v_add_u32_e32 v203, s16, v202
	v_mul_hi_i32 v226, v203, s3
	v_add_u32_e32 v226, v226, v203
	v_lshrrev_b32_e32 v227, 31, v226
	v_ashrrev_i32_e32 v226, 15, v226
	v_add_u32_e32 v226, v226, v227
	v_mul_i32_i24_e32 v227, 0xfe00, v226
	v_sub_u32_e32 v227, v203, v227
	v_lshlrev_b32_e32 v226, 20, v226
	v_lshl_add_u32 v211, v227, 4, v226
	v_cmp_ge_i32_e64 s[54:55], s12, v203
	s_and_b64 s[54:55], s[54:55], s[86:87]
	s_mov_b64 exec, s[54:55]
	v_add_u32_e32 v228, 0x2000, v211
	global_load_dwordx4 v[172:175], v228, s[6:7]
	s_mov_b64 exec, s[86:87]
	v_add_u32_e32 v204, s16, v203
	v_mul_hi_i32 v226, v204, s3
	v_add_u32_e32 v226, v226, v204
	v_lshrrev_b32_e32 v227, 31, v226
	v_ashrrev_i32_e32 v226, 15, v226
	v_add_u32_e32 v226, v226, v227
	v_mul_i32_i24_e32 v227, 0xfe00, v226
	v_sub_u32_e32 v227, v204, v227
	v_lshlrev_b32_e32 v226, 20, v226
	v_lshl_add_u32 v212, v227, 4, v226
	v_cmp_ge_i32_e64 s[56:57], s12, v204
	s_and_b64 s[56:57], s[56:57], s[86:87]
	s_mov_b64 exec, s[56:57]
	v_add_u32_e32 v228, 0x2000, v212
	global_load_dwordx4 v[176:179], v228, s[6:7]
	s_mov_b64 exec, s[86:87]
	v_add_u32_e32 v205, s16, v204
	v_mul_hi_i32 v226, v205, s3
	v_add_u32_e32 v226, v226, v205
	v_lshrrev_b32_e32 v227, 31, v226
	v_ashrrev_i32_e32 v226, 15, v226
	v_add_u32_e32 v226, v226, v227
	v_mul_i32_i24_e32 v227, 0xfe00, v226
	v_sub_u32_e32 v227, v205, v227
	v_lshlrev_b32_e32 v226, 20, v226
	v_lshl_add_u32 v213, v227, 4, v226
	v_cmp_ge_i32_e64 s[58:59], s12, v205
	s_and_b64 s[58:59], s[58:59], s[86:87]
	s_mov_b64 exec, s[58:59]
	v_add_u32_e32 v228, 0x2000, v213
	global_load_dwordx4 v[180:183], v228, s[6:7]
	s_mov_b64 exec, s[86:87]
	v_add_u32_e32 v206, s16, v205
	v_mul_hi_i32 v226, v206, s3
	v_add_u32_e32 v226, v226, v206
	v_lshrrev_b32_e32 v227, 31, v226
	v_ashrrev_i32_e32 v226, 15, v226
	v_add_u32_e32 v226, v226, v227
	v_mul_i32_i24_e32 v227, 0xfe00, v226
	v_sub_u32_e32 v227, v206, v227
	v_lshlrev_b32_e32 v226, 20, v226
	v_lshl_add_u32 v214, v227, 4, v226
	v_cmp_ge_i32_e64 s[60:61], s12, v206
	s_and_b64 s[60:61], s[60:61], s[86:87]
	s_mov_b64 exec, s[60:61]
	v_add_u32_e32 v228, 0x2000, v214
	global_load_dwordx4 v[184:187], v228, s[6:7]
	s_mov_b64 exec, s[86:87]
	v_add_u32_e32 v207, s16, v206
	v_mul_hi_i32 v226, v207, s3
	v_add_u32_e32 v226, v226, v207
	v_lshrrev_b32_e32 v227, 31, v226
	v_ashrrev_i32_e32 v226, 15, v226
	v_add_u32_e32 v226, v226, v227
	v_mul_i32_i24_e32 v227, 0xfe00, v226
	v_sub_u32_e32 v227, v207, v227
	v_lshlrev_b32_e32 v226, 20, v226
	v_lshl_add_u32 v215, v227, 4, v226
	v_cmp_ge_i32_e64 s[62:63], s12, v207
	s_and_b64 s[62:63], s[62:63], s[86:87]
	s_mov_b64 exec, s[62:63]
	v_add_u32_e32 v228, 0x2000, v215
	global_load_dwordx4 v[188:191], v228, s[6:7]
	s_mov_b64 exec, s[86:87]
	v_add_u32_e32 v208, s16, v207
	v_mul_hi_i32 v226, v208, s3
	v_add_u32_e32 v226, v226, v208
	v_lshrrev_b32_e32 v227, 31, v226
	v_ashrrev_i32_e32 v226, 15, v226
	v_add_u32_e32 v226, v226, v227
	v_mul_i32_i24_e32 v227, 0xfe00, v226
	v_sub_u32_e32 v227, v208, v227
	v_lshlrev_b32_e32 v226, 20, v226
	v_lshl_add_u32 v216, v227, 4, v226
	v_cmp_ge_i32_e64 s[64:65], s12, v208
	s_and_b64 s[64:65], s[64:65], s[86:87]
	s_mov_b64 exec, s[64:65]
	v_add_u32_e32 v228, 0x2000, v216
	global_load_dwordx4 v[192:195], v228, s[6:7]
	s_mov_b64 exec, s[86:87]
	s_waitcnt vmcnt(0)
	s_mov_b64 exec, s[50:51]
	global_store_dwordx4 v209, v[164:167], s[8:9]
	s_mov_b64 exec, s[52:53]
	global_store_dwordx4 v210, v[168:171], s[8:9]
	s_mov_b64 exec, s[54:55]
	global_store_dwordx4 v211, v[172:175], s[8:9]
	s_mov_b64 exec, s[56:57]
	global_store_dwordx4 v212, v[176:179], s[8:9]
	s_mov_b64 exec, s[58:59]
	global_store_dwordx4 v213, v[180:183], s[8:9]
	s_mov_b64 exec, s[60:61]
	global_store_dwordx4 v214, v[184:187], s[8:9]
	s_mov_b64 exec, s[62:63]
	global_store_dwordx4 v215, v[188:191], s[8:9]
	s_mov_b64 exec, s[64:65]
	global_store_dwordx4 v216, v[192:195], s[8:9]
	s_mov_b64 exec, s[86:87]
	v_add_u32_e32 v1, s16, v208
	v_cmp_ge_i32_e32 vcc, s12, v1
	s_cbranch_vccnz .Lp0_wc_loop
.LBB0_202:
	s_or_b64 exec, exec, s[4:5]
	s_mov_b32 s3, 0x440000
	v_cmp_gt_i32_e32 vcc, s3, v72
	s_and_saveexec_b64 s[4:5], vcc
	s_cbranch_execz .LBB0_213
	s_add_u32 s6, s30, 0x3ea53000
	s_addc_u32 s7, s31, 0
	s_add_u32 s88, s30, 0x3e1d3000
	s_addc_u32 s89, s31, 0
	s_mov_b64 s[20:21], s[0:1]
	s_load_dwordx2 s[20:21], s[20:21], 0x18
	s_mov_b32 s3, 0x78787879
	s_movk_i32 s17, 0x1ff
	s_movk_i32 s22, 0x203
	s_movk_i32 s23, 0x7fff
	s_mov_b32 s25, 0x43ffff
	v_lshlrev_b32_e32 v6, 2, v146
	v_mov_b32_e32 v5, 0
	s_mov_b64 s[86:87], exec
	s_waitcnt lgkmcnt(0)
.Lp0_sw_loop:
	v_mov_b32_e32 v201, v72
	v_ashrrev_i32_e32 v226, 6, v201
	v_mul_hi_i32 v217, v226, s3
	v_lshrrev_b32_e32 v227, 31, v217
	v_ashrrev_i32_e32 v217, 8, v217
	v_add_u32_e32 v217, v217, v227
	v_mul_i32_i24_e32 v227, 0x220, v217
	v_sub_u32_e32 v209, v226, v227
	v_cmp_ge_i32_e64 s[84:85], s25, v201
	s_and_b64 s[84:85], s[84:85], s[86:87]
	v_cmp_ge_i32_e64 s[50:51], s17, v209
	v_cmp_lt_i32_e64 s[66:67], s22, v209
	s_and_b64 s[50:51], s[50:51], s[84:85]
	s_and_b64 s[66:67], s[66:67], s[84:85]
	v_ashrrev_i32_e32 v226, 2, v217
	v_lshlrev_b32_e32 v226, 20, v226
	v_lshl_or_b32 v226, v209, 11, v226
	v_and_b32_e32 v227, 3, v217
	v_lshl_or_b32 v226, v227, 8, v226
	v_or_b32_e32 v226, v226, v6
	s_mov_b64 exec, s[50:51]
	global_load_dword v180, v226, s[20:21]
	global_load_dword v188, v226, s[20:21] offset:1024
	s_mov_b64 exec, s[86:87]
	v_add_u32_e32 v202, s16, v201
	v_ashrrev_i32_e32 v226, 6, v202
	v_mul_hi_i32 v218, v226, s3
	v_lshrrev_b32_e32 v227, 31, v218
	v_ashrrev_i32_e32 v218, 8, v218
	v_add_u32_e32 v218, v218, v227
	v_mul_i32_i24_e32 v227, 0x220, v218
	v_sub_u32_e32 v210, v226, v227
	v_cmp_ge_i32_e64 s[84:85], s25, v202
	s_and_b64 s[84:85], s[84:85], s[86:87]
	v_cmp_ge_i32_e64 s[52:53], s17, v210
	v_cmp_lt_i32_e64 s[68:69], s22, v210
	s_and_b64 s[52:53], s[52:53], s[84:85]
	s_and_b64 s[68:69], s[68:69], s[84:85]
	v_ashrrev_i32_e32 v226, 2, v218
	v_lshlrev_b32_e32 v226, 20, v226
	v_lshl_or_b32 v226, v210, 11, v226
	v_and_b32_e32 v227, 3, v218
	v_lshl_or_b32 v226, v227, 8, v226
	v_or_b32_e32 v226, v226, v6
	s_mov_b64 exec, s[52:53]
	global_load_dword v181, v226, s[20:21]
	global_load_dword v189, v226, s[20:21] offset:1024
	s_mov_b64 exec, s[86:87]
	v_add_u32_e32 v203, s16, v202
	v_ashrrev_i32_e32 v226, 6, v203
	v_mul_hi_i32 v219, v226, s3
	v_lshrrev_b32_e32 v227, 31, v219
	v_ashrrev_i32_e32 v219, 8, v219
	v_add_u32_e32 v219, v219, v227
	v_mul_i32_i24_e32 v227, 0x220, v219
	v_sub_u32_e32 v211, v226, v227
	v_cmp_ge_i32_e64 s[84:85], s25, v203
	s_and_b64 s[84:85], s[84:85], s[86:87]
	v_cmp_ge_i32_e64 s[54:55], s17, v211
	v_cmp_lt_i32_e64 s[70:71], s22, v211
	s_and_b64 s[54:55], s[54:55], s[84:85]
	s_and_b64 s[70:71], s[70:71], s[84:85]
	v_ashrrev_i32_e32 v226, 2, v219
	v_lshlrev_b32_e32 v226, 20, v226
	v_lshl_or_b32 v226, v211, 11, v226
	v_and_b32_e32 v227, 3, v219
	v_lshl_or_b32 v226, v227, 8, v226
	v_or_b32_e32 v226, v226, v6
	s_mov_b64 exec, s[54:55]
	global_load_dword v182, v226, s[20:21]
	global_load_dword v190, v226, s[20:21] offset:1024
	s_mov_b64 exec, s[86:87]
	v_add_u32_e32 v204, s16, v203
	v_ashrrev_i32_e32 v226, 6, v204
	v_mul_hi_i32 v220, v226, s3
	v_lshrrev_b32_e32 v227, 31, v220
	v_ashrrev_i32_e32 v220, 8, v220
	v_add_u32_e32 v220, v220, v227
	v_mul_i32_i24_e32 v227, 0x220, v220
	v_sub_u32_e32 v212, v226, v227
	v_cmp_ge_i32_e64 s[84:85], s25, v204
	s_and_b64 s[84:85], s[84:85], s[86:87]
	v_cmp_ge_i32_e64 s[56:57], s17, v212
	v_cmp_lt_i32_e64 s[72:73], s22, v212
	s_and_b64 s[56:57], s[56:57], s[84:85]
	s_and_b64 s[72:73], s[72:73], s[84:85]
	v_ashrrev_i32_e32 v226, 2, v220
	v_lshlrev_b32_e32 v226, 20, v226
	v_lshl_or_b32 v226, v212, 11, v226
	v_and_b32_e32 v227, 3, v220
	v_lshl_or_b32 v226, v227, 8, v226
	v_or_b32_e32 v226, v226, v6
	s_mov_b64 exec, s[56:57]
	global_load_dword v183, v226, s[20:21]
	global_load_dword v191, v226, s[20:21] offset:1024
	s_mov_b64 exec, s[86:87]
	v_add_u32_e32 v205, s16, v204
	v_ashrrev_i32_e32 v226, 6, v205
	v_mul_hi_i32 v221, v226, s3
	v_lshrrev_b32_e32 v227, 31, v221
	v_ashrrev_i32_e32 v221, 8, v221
	v_add_u32_e32 v221, v221, v227
	v_mul_i32_i24_e32 v227, 0x220, v221
	v_sub_u32_e32 v213, v226, v227
	v_cmp_ge_i32_e64 s[84:85], s25, v205
	s_and_b64 s[84:85], s[84:85], s[86:87]
	v_cmp_ge_i32_e64 s[58:59], s17, v213
	v_cmp_lt_i32_e64 s[74:75], s22, v213
	s_and_b64 s[58:59], s[58:59], s[84:85]
	s_and_b64 s[74:75], s[74:75], s[84:85]
	v_ashrrev_i32_e32 v226, 2, v221
	v_lshlrev_b32_e32 v226, 20, v226
	v_lshl_or_b32 v226, v213, 11, v226
	v_and_b32_e32 v227, 3, v221
	v_lshl_or_b32 v226, v227, 8, v226
	v_or_b32_e32 v226, v226, v6
	s_mov_b64 exec, s[58:59]
	global_load_dword v184, v226, s[20:21]
	global_load_dword v192, v226, s[20:21] offset:1024
	s_mov_b64 exec, s[86:87]
	v_add_u32_e32 v206, s16, v205
	v_ashrrev_i32_e32 v226, 6, v206
	v_mul_hi_i32 v222, v226, s3
	v_lshrrev_b32_e32 v227, 31, v222
	v_ashrrev_i32_e32 v222, 8, v222
	v_add_u32_e32 v222, v222, v227
	v_mul_i32_i24_e32 v227, 0x220, v222
	v_sub_u32_e32 v214, v226, v227
	v_cmp_ge_i32_e64 s[84:85], s25, v206
	s_and_b64 s[84:85], s[84:85], s[86:87]
	v_cmp_ge_i32_e64 s[60:61], s17, v214
	v_cmp_lt_i32_e64 s[76:77], s22, v214
	s_and_b64 s[60:61], s[60:61], s[84:85]
	s_and_b64 s[76:77], s[76:77], s[84:85]
	v_ashrrev_i32_e32 v226, 2, v222
	v_lshlrev_b32_e32 v226, 20, v226
	v_lshl_or_b32 v226, v214, 11, v226
	v_and_b32_e32 v227, 3, v222
	v_lshl_or_b32 v226, v227, 8, v226
	v_or_b32_e32 v226, v226, v6
	s_mov_b64 exec, s[60:61]
	global_load_dword v185, v226, s[20:21]
	global_load_dword v193, v226, s[20:21] offset:1024
	s_mov_b64 exec, s[86:87]
	v_add_u32_e32 v207, s16, v206
	v_ashrrev_i32_e32 v226, 6, v207
	v_mul_hi_i32 v223, v226, s3
	v_lshrrev_b32_e32 v227, 31, v223
	v_ashrrev_i32_e32 v223, 8, v223
	v_add_u32_e32 v223, v223, v227
	v_mul_i32_i24_e32 v227, 0x220, v223
	v_sub_u32_e32 v215, v226, v227
	v_cmp_ge_i32_e64 s[84:85], s25, v207
	s_and_b64 s[84:85], s[84:85], s[86:87]
	v_cmp_ge_i32_e64 s[62:63], s17, v215
	v_cmp_lt_i32_e64 s[78:79], s22, v215
	s_and_b64 s[62:63], s[62:63], s[84:85]
	s_and_b64 s[78:79], s[78:79], s[84:85]
	v_ashrrev_i32_e32 v226, 2, v223
	v_lshlrev_b32_e32 v226, 20, v226
	v_lshl_or_b32 v226, v215, 11, v226
	v_and_b32_e32 v227, 3, v223
	v_lshl_or_b32 v226, v227, 8, v226
	v_or_b32_e32 v226, v226, v6
	s_mov_b64 exec, s[62:63]
	global_load_dword v186, v226, s[20:21]
	global_load_dword v194, v226, s[20:21] offset:1024
	s_mov_b64 exec, s[86:87]
	v_add_u32_e32 v208, s16, v207
	v_ashrrev_i32_e32 v226, 6, v208
	v_mul_hi_i32 v224, v226, s3
	v_lshrrev_b32_e32 v227, 31, v224
	v_ashrrev_i32_e32 v224, 8, v224
	v_add_u32_e32 v224, v224, v227
	v_mul_i32_i24_e32 v227, 0x220, v224
	v_sub_u32_e32 v216, v226, v227
	v_cmp_ge_i32_e64 s[84:85], s25, v208
	s_and_b64 s[84:85], s[84:85], s[86:87]
	v_cmp_ge_i32_e64 s[64:65], s17, v216
	v_cmp_lt_i32_e64 s[80:81], s22, v216
	s_and_b64 s[64:65], s[64:65], s[84:85]
	s_and_b64 s[80:81], s[80:81], s[84:85]
	v_ashrrev_i32_e32 v226, 2, v224
	v_lshlrev_b32_e32 v226, 20, v226
	v_lshl_or_b32 v226, v216, 11, v226
	v_and_b32_e32 v227, 3, v224
	v_lshl_or_b32 v226, v227, 8, v226
	v_or_b32_e32 v226, v226, v6
	s_mov_b64 exec, s[64:65]
	global_load_dword v187, v226, s[20:21]
	global_load_dword v195, v226, s[20:21] offset:1024
	s_mov_b64 exec, s[86:87]
	s_waitcnt vmcnt(0)
	v_lshlrev_b32_e32 v226, 1, v201
	v_lshl_or_b32 v227, v217, 6, v146
	v_mul_u32_u24_e32 v227, 0x440, v227
	v_lshl_add_u32 v227, v209, 1, v227
	v_bfe_u32 v228, v180, 16, 1
	v_bfe_u32 v229, v188, 16, 1
	v_add3_u32 v228, v180, v228, s23
	v_add3_u32 v229, v188, v229, s23
	s_mov_b64 exec, s[50:51]
	global_store_short_d16_hi v226, v228, s[88:89]
	global_store_short_d16_hi v227, v229, s[6:7]
	s_mov_b64 exec, s[66:67]
	global_store_short v226, v5, s[88:89]
	global_store_short v227, v5, s[6:7]
	s_mov_b64 exec, s[86:87]
	v_lshlrev_b32_e32 v226, 1, v202
	v_lshl_or_b32 v227, v218, 6, v146
	v_mul_u32_u24_e32 v227, 0x440, v227
	v_lshl_add_u32 v227, v210, 1, v227
	v_bfe_u32 v228, v181, 16, 1
	v_bfe_u32 v229, v189, 16, 1
	v_add3_u32 v228, v181, v228, s23
	v_add3_u32 v229, v189, v229, s23
	s_mov_b64 exec, s[52:53]
	global_store_short_d16_hi v226, v228, s[88:89]
	global_store_short_d16_hi v227, v229, s[6:7]
	s_mov_b64 exec, s[68:69]
	global_store_short v226, v5, s[88:89]
	global_store_short v227, v5, s[6:7]
	s_mov_b64 exec, s[86:87]
	v_lshlrev_b32_e32 v226, 1, v203
	v_lshl_or_b32 v227, v219, 6, v146
	v_mul_u32_u24_e32 v227, 0x440, v227
	v_lshl_add_u32 v227, v211, 1, v227
	v_bfe_u32 v228, v182, 16, 1
	v_bfe_u32 v229, v190, 16, 1
	v_add3_u32 v228, v182, v228, s23
	v_add3_u32 v229, v190, v229, s23
	s_mov_b64 exec, s[54:55]
	global_store_short_d16_hi v226, v228, s[88:89]
	global_store_short_d16_hi v227, v229, s[6:7]
	s_mov_b64 exec, s[70:71]
	global_store_short v226, v5, s[88:89]
	global_store_short v227, v5, s[6:7]
	s_mov_b64 exec, s[86:87]
	v_lshlrev_b32_e32 v226, 1, v204
	v_lshl_or_b32 v227, v220, 6, v146
	v_mul_u32_u24_e32 v227, 0x440, v227
	v_lshl_add_u32 v227, v212, 1, v227
	v_bfe_u32 v228, v183, 16, 1
	v_bfe_u32 v229, v191, 16, 1
	v_add3_u32 v228, v183, v228, s23
	v_add3_u32 v229, v191, v229, s23
	s_mov_b64 exec, s[56:57]
	global_store_short_d16_hi v226, v228, s[88:89]
	global_store_short_d16_hi v227, v229, s[6:7]
	s_mov_b64 exec, s[72:73]
	global_store_short v226, v5, s[88:89]
	global_store_short v227, v5, s[6:7]
	s_mov_b64 exec, s[86:87]
	v_lshlrev_b32_e32 v226, 1, v205
	v_lshl_or_b32 v227, v221, 6, v146
	v_mul_u32_u24_e32 v227, 0x440, v227
	v_lshl_add_u32 v227, v213, 1, v227
	v_bfe_u32 v228, v184, 16, 1
	v_bfe_u32 v229, v192, 16, 1
	v_add3_u32 v228, v184, v228, s23
	v_add3_u32 v229, v192, v229, s23
	s_mov_b64 exec, s[58:59]
	global_store_short_d16_hi v226, v228, s[88:89]
	global_store_short_d16_hi v227, v229, s[6:7]
	s_mov_b64 exec, s[74:75]
	global_store_short v226, v5, s[88:89]
	global_store_short v227, v5, s[6:7]
	s_mov_b64 exec, s[86:87]
	v_lshlrev_b32_e32 v226, 1, v206
	v_lshl_or_b32 v227, v222, 6, v146
	v_mul_u32_u24_e32 v227, 0x440, v227
	v_lshl_add_u32 v227, v214, 1, v227
	v_bfe_u32 v228, v185, 16, 1
	v_bfe_u32 v229, v193, 16, 1
	v_add3_u32 v228, v185, v228, s23
	v_add3_u32 v229, v193, v229, s23
	s_mov_b64 exec, s[60:61]
	global_store_short_d16_hi v226, v228, s[88:89]
	global_store_short_d16_hi v227, v229, s[6:7]
	s_mov_b64 exec, s[76:77]
	global_store_short v226, v5, s[88:89]
	global_store_short v227, v5, s[6:7]
	s_mov_b64 exec, s[86:87]
	v_lshlrev_b32_e32 v226, 1, v207
	v_lshl_or_b32 v227, v223, 6, v146
	v_mul_u32_u24_e32 v227, 0x440, v227
	v_lshl_add_u32 v227, v215, 1, v227
	v_bfe_u32 v228, v186, 16, 1
	v_bfe_u32 v229, v194, 16, 1
	v_add3_u32 v228, v186, v228, s23
	v_add3_u32 v229, v194, v229, s23
	s_mov_b64 exec, s[62:63]
	global_store_short_d16_hi v226, v228, s[88:89]
	global_store_short_d16_hi v227, v229, s[6:7]
	s_mov_b64 exec, s[78:79]
	global_store_short v226, v5, s[88:89]
	global_store_short v227, v5, s[6:7]
	s_mov_b64 exec, s[86:87]
	v_lshlrev_b32_e32 v226, 1, v208
	v_lshl_or_b32 v227, v224, 6, v146
	v_mul_u32_u24_e32 v227, 0x440, v227
	v_lshl_add_u32 v227, v216, 1, v227
	v_bfe_u32 v228, v187, 16, 1
	v_bfe_u32 v229, v195, 16, 1
	v_add3_u32 v228, v187, v228, s23
	v_add3_u32 v229, v195, v229, s23
	s_mov_b64 exec, s[64:65]
	global_store_short_d16_hi v226, v228, s[88:89]
	global_store_short_d16_hi v227, v229, s[6:7]
	s_mov_b64 exec, s[80:81]
	global_store_short v226, v5, s[88:89]
	global_store_short v227, v5, s[6:7]
	s_mov_b64 exec, s[86:87]
	v_add_u32_e32 v72, s16, v208
	v_cmp_ge_i32_e32 vcc, s25, v72
	s_cbranch_vccnz .Lp0_sw_loop
